# polarity flip: kernel-wide static s_setprio 1 for waves 0-3 instead of 4-7, GEMM toggles deleted
# baseline (speedup 1.0000x reference)
; #define LAS __attribute__((address_space(3)))
; #define PG8_LAS __attribute__((address_space(3)))
; __global__ void __launch_bounds__(NTHREADS, 2) fwd_megakernel(Args a) {
;     extern __shared__ __attribute__((aligned(16))) unsigned char lds[];
;     cg::grid_group grid = cg::this_grid();
;     PG8_LAS unsigned char* ldsg = (PG8_LAS unsigned char*)lds;
;     const int G = gridDim.x, bx = blockIdx.x;
;     bf16_t* wt = (bf16_t*)(a.ws + OFF_WT);
;     bf16_t* hbuf = (bf16_t*)(a.ws + OFF_H);
;     bf16_t* r1 = (bf16_t*)(a.ws + OFF_R1); bf16_t* r2 = (bf16_t*)(a.ws + OFF_R2); bf16_t* r3 = (bf16_t*)(a.ws + OFF_R3); bf16_t* r4 = (bf16_t*)(a.ws + OFF_R4);
;     { volatile LAS unsigned* bst = (volatile LAS unsigned*)((LAS unsigned char*)lds + LDS_MAIN);
;       if (threadIdx.x < 4) bst[threadIdx.x] = 0u;
;       __syncthreads();
;       (void)xcd_barrier_post((unsigned*)(a.ws + OFF_BAR), bst); }
_Z14fwd_megakernel4Args:
	s_mov_b32 s68, s2
	s_load_dwordx8 s[24:31], s[0:1], 0x80
	s_load_dword s2, s[0:1], 0xa0
	v_and_b32_e32 v252, 0x3ff, v0
	v_cmp_gt_u32_e32 vcc, 4, v252
	s_waitcnt lgkmcnt(0)
	v_writelane_b32 v253, s2, 0
	s_add_u32 s2, s0, 0x98
	s_addc_u32 s3, s1, 0
	v_writelane_b32 v253, s2, 1
	s_nop 1
	v_writelane_b32 v253, s3, 2
	s_and_saveexec_b64 s[4:5], vcc
	v_lshl_add_u32 v1, v252, 2, 0
	v_add_u32_e32 v1, 0x20000, v1
	v_mov_b32_e32 v2, 0
	ds_write_b32 v1, v2
	s_or_b64 exec, exec, s[4:5]
	v_readfirstlane_b32 s100, v252
	s_nop 3
	s_lshr_b32 s100, s100, 6
	s_cmp_ge_u32 s100, 4
	s_cbranch_scc1 .Lk_prio_done
	s_setprio 1

; DI unsigned cvtpk(float lo, float hi) { unsigned r; asm volatile("v_cvt_pk_bf16_f32 %0, %1, %2" : "=v"(r) : "v"(lo), "v"(hi)); return r; }
; DI int v_st(int k, int c) { const int kk = (k & ~0xC) | ((k & 4) << 1) | ((k & 8) >> 1); return ((kk >> 3) * 4 + (c >> 5)) * 512 + ((kk & 7) * 32 + (c & 31)) * 2; }
; DI int v_rd_base(int lane) { return ((lane & 3) << 3) | (((lane >> 2) & 3) << 6) | (((lane >> 4) & 1) << 5) | (((lane >> 5) & 1) << 8); }
; #define SLOAD(i, k0) do { sr_[i].vs0 = ld8(&Vh[(long)((k0) + sr) * LDK + sc]); sr_[i].vs1 = ld8(&Vh[(long)((k0) + 32 + sr) * LDK + sc]); \
;     sr_[i].ks0 = ld8(&Kh[(long)((k0) + sr) * LDK + sc]); sr_[i].ks1 = ld8(&Kh[(long)((k0) + 32 + sr) * LDK + sc]); } while (0)
; DI void qkt(f32x16& p0, f32x16& p1, const bf16_t* Ks, const bf16x8* qr, int r32, int hi) {
;   p0 = f32x16{}; p1 = f32x16{};
;   for (int d0 = 0; d0 < 8; ++d0) { int cb = (d0 * 16 + hi * 8) * 2;
;     bf16x8 b0 = *reinterpret_cast<const bf16x8*>((const char*)Ks + KSWZ(r32, cb));
;     bf16x8 b1 = *reinterpret_cast<const bf16x8*>((const char*)Ks + KSWZ(32 + r32, cb));
;     p0 = __builtin_amdgcn_mfma_f32_32x32x16_bf16(b0, qr[d0], p0, 0, 0, 0);
;     p1 = __builtin_amdgcn_mfma_f32_32x32x16_bf16(b1, qr[d0], p1, 0, 0, 0); }
; DI void attn_dense_body(const bf16_t* __restrict__ Qb, const bf16_t* __restrict__ Kh, const bf16_t* __restrict__ Vh, ...
;     ...
;     for (int d0 = 0; d0 < 8; ++d0) { u32x4 w = {cvtpk(xf[d0][0], xf[d0][1]), cvtpk(xf[d0][2], xf[d0][3]), cvtpk(xf[d0][4], xf[d0][5]), cvtpk(xf[d0][6], xf[d0][7])}; qr[d0] = *reinterpret_cast<bf16x8*>(&w); }
;     ...
;   const int sr = tid >> 4, sc = (tid & 15) * 8, vst0 = v_st(sr, sc), vst1 = v_st(32 + sr, sc);
;   const int vb0 = (int)(uintptr_t)V_lds + v_rd_base(lane);
;   struct { bf16x8 vs0, vs1, ks0, ks1; } sr_[2];
;     ...
;   f32x16 pA0, pA1, pB0, pB1; float mnA, mnB, alA, alB; bf16x8 pa0, pa1, pa2, pa3; const int NT = seq / KVBLK;
;   constexpr int SE = 0, SO = 1;
;   SLOAD(SE, 0); asm volatile("s_waitcnt vmcnt(0)" ::: "memory"); SWRITE(0, SE); __syncthreads();
;   qkt(pA0, pA1, K_lds, qr, r32, hi); partialSM(pA0, pA1, m_reg, mnA, alA);
.LBB0_834:
	s_or_b32 s4, s0, s12
	s_mov_b32 s5, s1
	s_lshl_b64 s[10:11], s[4:5], 1
	v_ashrrev_i32_e32 v176, 4, v160
	s_add_u32 s4, s96, s10
	v_cvt_pk_bf16_f32 v116, v114, v113
	v_cvt_pk_bf16_f32 v117, v106, v105
	v_cvt_pk_bf16_f32 v118, v98, v55
	v_cvt_pk_bf16_f32 v119, v90, v65
	v_cvt_pk_bf16_f32 v124, v88, v67
	v_cvt_pk_bf16_f32 v125, v86, v73
	v_cvt_pk_bf16_f32 v126, v84, v79
	v_cvt_pk_bf16_f32 v127, v82, v81
	v_cvt_pk_bf16_f32 v120, v40, v41
	v_cvt_pk_bf16_f32 v121, v42, v43
	v_cvt_pk_bf16_f32 v122, v44, v45
	v_cvt_pk_bf16_f32 v123, v46, v47
	v_cvt_pk_bf16_f32 v112, v56, v57
	v_cvt_pk_bf16_f32 v113, v58, v59
	v_cvt_pk_bf16_f32 v114, v60, v61
	v_cvt_pk_bf16_f32 v115, v62, v63
	v_cvt_pk_bf16_f32 v108, v76, v77
	v_cvt_pk_bf16_f32 v109, v74, v75
	v_cvt_pk_bf16_f32 v110, v70, v71
	v_cvt_pk_bf16_f32 v111, v68, v69
	v_cvt_pk_bf16_f32 v104, v38, v39
	v_cvt_pk_bf16_f32 v105, v36, v37
	v_cvt_pk_bf16_f32 v106, v34, v35
	v_cvt_pk_bf16_f32 v107, v32, v33
	v_cvt_pk_bf16_f32 v100, v28, v29
	v_cvt_pk_bf16_f32 v101, v30, v31
	v_cvt_pk_bf16_f32 v102, v18, v19
	v_cvt_pk_bf16_f32 v103, v20, v21
	v_cvt_pk_bf16_f32 v96, v22, v23
	v_cvt_pk_bf16_f32 v97, v26, v27
	v_cvt_pk_bf16_f32 v98, v16, v17
	v_lshlrev_b32_e32 v16, 3, v160
	v_add_u32_e32 v184, 32, v176
	s_addc_u32 s5, s97, s11
	v_readlane_b32 s13, v254, 38
	v_and_b32_e32 v178, 0x78, v16
	v_ashrrev_i32_e32 v177, 31, v176
	v_ashrrev_i32_e32 v185, 31, v184
	s_add_u32 s10, s13, s10
	v_readlane_b32 s13, v254, 39
	v_lshlrev_b32_e32 v72, 1, v178
	v_lshlrev_b64 v[48:49], 9, v[176:177]
	v_lshlrev_b64 v[12:13], 9, v[184:185]
	s_addc_u32 s11, s13, s11
	v_or_b32_e32 v8, v48, v72
	v_mov_b32_e32 v9, v49
	v_or_b32_e32 v12, v12, v72
	v_lshl_add_u64 v[0:1], s[10:11], 0, v[8:9]
	v_lshl_add_u64 v[4:5], s[10:11], 0, v[12:13]
	v_cvt_pk_bf16_f32 v99, v24, v25
	global_load_dwordx4 v[0:3], v[0:1], off
	s_nop 0
	global_load_dwordx4 v[4:7], v[4:5], off
	v_lshl_add_u64 v[8:9], s[4:5], 0, v[8:9]
	global_load_dwordx4 v[8:11], v[8:9], off
	v_lshl_add_u64 v[12:13], s[4:5], 0, v[12:13]
	global_load_dwordx4 v[12:15], v[12:13], off
	v_and_b32_e32 v18, 0xfffff0, v176
	v_lshlrev_b32_e32 v19, 1, v176
	v_lshrrev_b32_e32 v20, 1, v176
	v_and_b32_e32 v21, 3, v176
	v_and_or_b32 v18, v19, 8, v18
	v_and_or_b32 v19, v20, 4, v21
	v_and_b32_e32 v20, 0xfffff0, v184
	v_lshlrev_b32_e32 v21, 1, v184
	v_bfe_u32 v16, v16, 5, 2
	v_lshrrev_b32_e32 v18, 1, v18
	v_and_or_b32 v20, v21, 8, v20
	v_or_b32_e32 v18, v18, v16
	v_lshrrev_b32_e32 v20, 1, v20
	v_lshlrev_b32_e32 v19, 6, v19
	v_and_b32_e32 v23, 48, v72
	v_lshlrev_b32_e32 v18, 9, v18
	v_or_b32_e32 v16, v20, v16
	v_and_b32_e32 v17, 0x70, v160
	v_lshrrev_b32_e32 v24, 1, v160
	v_and_b32_e32 v24, 0x80, v24
	v_or_b32_e32 v17, v17, v24
	v_lshlrev_b32_e32 v22, 8, v176
	v_or3_b32 v18, v18, v19, v23
	v_lshlrev_b32_e32 v16, 9, v16
	v_bitop3_b32 v21, v72, v22, v17 bitop3:0xde
	v_or3_b32 v16, v16, v19, v23
	v_add_u32_e32 v204, 0, v18
	v_add_u32_e32 v203, 0, v21
	s_waitcnt vmcnt(0)
	v_add_u32_e32 v205, 0, v16
	s_waitcnt vmcnt(3)
	ds_write_b128 v204, v[0:3]
	s_waitcnt vmcnt(2)
	ds_write_b128 v205, v[4:7]
	s_waitcnt vmcnt(1)
	ds_write_b128 v203, v[8:11] offset:32768
	v_lshlrev_b32_e32 v0, 8, v184
	v_bitop3_b32 v0, v72, v0, v17 bitop3:0xde
	v_add_u32_e32 v206, 0, v0
	v_lshlrev_b32_e32 v0, 4, v196
	v_lshlrev_b32_e32 v66, 8, v196
	v_and_b32_e32 v67, 0x70, v0
	v_lshrrev_b32_e32 v24, 1, v0
	v_and_b32_e32 v24, 0x80, v24
	v_or_b32_e32 v67, v67, v24
	v_bitop3_b32 v0, v180, v66, v67 bitop3:0xde
	v_add_u32_e32 v207, 0, v0
	s_waitcnt vmcnt(0)
	ds_write_b128 v206, v[12:15] offset:32768
	s_waitcnt lgkmcnt(0)
	s_barrier
	ds_read_b128 v[0:3], v207 offset:32768
	ds_read_b128 v[4:7], v207 offset:40960
	s_waitcnt lgkmcnt(1)
	v_mfma_f32_32x32x16_bf16 v[16:31], v[0:3], v[116:119], 0
	v_or_b32_e32 v0, 32, v180
	v_bitop3_b32 v0, v0, v66, v67 bitop3:0xde
	v_add_u32_e32 v210, 0, v0
	s_add_i32 s13, 0, 0x10000
	v_and_b32_e32 v74, 63, v160
	v_lshlrev_b32_e32 v68, 3, v74
	v_add_u32_e32 v186, 64, v176
	s_waitcnt lgkmcnt(0)
	v_mfma_f32_32x32x16_bf16 v[32:47], v[4:7], v[116:119], 0
	ds_read_b128 v[0:3], v210 offset:32768
	ds_read_b128 v[4:7], v210 offset:40960
	v_ashrrev_i32_e32 v187, 31, v186
	v_add_u32_e32 v188, 0x60, v176
	v_lshlrev_b64 v[8:9], 9, v[186:187]
	v_ashrrev_i32_e32 v189, 31, v188
	v_lshlrev_b32_e32 v70, 1, v74
	v_or_b32_e32 v8, v8, v72
	s_waitcnt lgkmcnt(1)
	v_mfma_f32_32x32x16_bf16 v[16:31], v[0:3], v[124:127], v[16:31]
	v_or_b32_e32 v0, 64, v180
	v_bitop3_b32 v0, v0, v66, v67 bitop3:0xde
	v_add_u32_e32 v211, 0, v0
	v_lshlrev_b64 v[12:13], 9, v[188:189]
	v_lshl_add_u64 v[10:11], s[10:11], 0, v[8:9]
	v_or_b32_e32 v12, v12, v72
	v_lshl_add_u64 v[8:9], s[4:5], 0, v[8:9]
	s_waitcnt lgkmcnt(0)
	v_mfma_f32_32x32x16_bf16 v[32:47], v[4:7], v[124:127], v[32:47]
	ds_read_b128 v[0:3], v211 offset:32768
	ds_read_b128 v[4:7], v211 offset:40960
	v_lshl_add_u64 v[14:15], s[10:11], 0, v[12:13]
	v_add_u32_e32 v190, 0x80, v176
	v_ashrrev_i32_e32 v191, 31, v190
	v_add_u32_e32 v192, 0xa0, v176
	v_ashrrev_i32_e32 v193, 31, v192
	s_cmp_lg_u32 0, -1
	s_waitcnt lgkmcnt(1)
	v_mfma_f32_32x32x16_bf16 v[16:31], v[0:3], v[120:123], v[16:31]
	v_or_b32_e32 v0, 0x60, v180
	v_bitop3_b32 v0, v0, v66, v67 bitop3:0xde
	v_add_u32_e32 v208, 0, v0
	s_mov_b32 s69, s68
	s_mov_b32 s70, s68
	s_mov_b32 s71, s68
	s_mov_b32 s72, s68
	s_waitcnt lgkmcnt(0)
	v_mfma_f32_32x32x16_bf16 v[32:47], v[4:7], v[120:123], v[32:47]
	ds_read_b128 v[0:3], v208 offset:32768
	ds_read_b128 v[4:7], v208 offset:40960
	s_mov_b32 s73, s68
	s_mov_b32 s74, s68
	s_mov_b32 s75, s68
	s_mov_b32 s76, s68
	s_mov_b32 s77, s68
	s_mov_b32 s78, s68
	s_waitcnt lgkmcnt(1)
; #define SLOAD(i, k0) do { sr_[i].vs0 = ld8(&Vh[(long)((k0) + sr) * LDK + sc]); sr_[i].vs1 = ld8(&Vh[(long)((k0) + 32 + sr) * LDK + sc]); \
;     sr_[i].ks0 = ld8(&Kh[(long)((k0) + sr) * LDK + sc]); sr_[i].ks1 = ld8(&Kh[(long)((k0) + 32 + sr) * LDK + sc]); } while (0)
; DI void partialSM(f32x16& p0, f32x16& p1, float& m_reg, float& mn, float& alpha) {
;     ...
;   float pmax = p0[0]; for (int r = 1; r < 16; ++r) pmax = fmaxf(pmax, p0[r]); for (int r = 0; r < 16; ++r) pmax = fmaxf(pmax, p1[r]);
;   { auto rr = __builtin_amdgcn_permlane32_swap(__float_as_uint(pmax), __float_as_uint(pmax), false, false);
;     pmax = fmaxf(__uint_as_float(rr[0]), __uint_as_float(rr[1])); }
; DI void qkt(f32x16& p0, f32x16& p1, const bf16_t* Ks, const bf16x8* qr, int r32, int hi) {
;   p0 = f32x16{}; p1 = f32x16{};
;   for (int d0 = 0; d0 < 8; ++d0) { int cb = (d0 * 16 + hi * 8) * 2;
;     bf16x8 b0 = *reinterpret_cast<const bf16x8*>((const char*)Ks + KSWZ(r32, cb));
;     bf16x8 b1 = *reinterpret_cast<const bf16x8*>((const char*)Ks + KSWZ(32 + r32, cb));
;     p0 = __builtin_amdgcn_mfma_f32_32x32x16_bf16(b0, qr[d0], p0, 0, 0, 0);
;     p1 = __builtin_amdgcn_mfma_f32_32x32x16_bf16(b1, qr[d0], p1, 0, 0, 0); }
; DI void attn_dense_body(const bf16_t* __restrict__ Qb, const bf16_t* __restrict__ Kh, const bf16_t* __restrict__ Vh, ...
;     ...
;   SLOAD(SO, KVBLK); if (2 < NT) SLOAD(SE, 2 * KVBLK);
	v_mfma_f32_32x32x16_bf16 v[16:31], v[0:3], v[112:115], v[16:31]
	v_or_b32_e32 v0, 0x80, v180
	v_bitop3_b32 v0, v0, v66, v67 bitop3:0xde
	v_add_u32_e32 v209, 0, v0
	ds_read_b128 v[0:3], v209 offset:32768
	s_mov_b32 s79, s68
	s_mov_b32 s80, s68
	s_mov_b32 s81, s68
	s_waitcnt lgkmcnt(1)
	v_mfma_f32_32x32x16_bf16 v[32:47], v[4:7], v[112:115], v[32:47]
	ds_read_b128 v[4:7], v209 offset:40960
	s_mov_b32 s82, s68
	s_mov_b32 s83, s68
	s_mov_b32 s16, 4
	v_mov_b32_e32 v200, 0
	s_waitcnt lgkmcnt(1)
	v_mfma_f32_32x32x16_bf16 v[16:31], v[0:3], v[108:111], v[16:31]
	v_and_b32_e32 v0, 0x3fffffc0, v160
	v_lshl_add_u32 v198, v0, 2, s13
	v_or_b32_e32 v0, 0xa0, v180
	v_bitop3_b32 v0, v0, v66, v67 bitop3:0xde
	v_add_u32_e32 v212, 0, v0
	ds_read_b128 v[0:3], v212 offset:32768
	s_cselect_b32 s13, 0, 0
	s_waitcnt lgkmcnt(1)
	v_mfma_f32_32x32x16_bf16 v[32:47], v[4:7], v[108:111], v[32:47]
	v_lshlrev_b32_e32 v4, 4, v74
	v_and_b32_e32 v4, 0xc0, v4
	v_and_or_b32 v69, v68, 24, v4
	ds_read_b128 v[4:7], v212 offset:40960
	v_lshl_add_u32 v199, v196, 2, v198
	s_waitcnt lgkmcnt(1)
	v_mfma_f32_32x32x16_bf16 v[16:31], v[0:3], v[104:107], v[16:31]
	v_or_b32_e32 v0, 0xc0, v180
	v_bitop3_b32 v0, v0, v66, v67 bitop3:0xde
	v_add_u32_e32 v213, 0, v0
	ds_read_b128 v[0:3], v213 offset:32768
	global_load_dwordx4 v[50:53], v[10:11], off
	global_load_dwordx4 v[54:57], v[14:15], off
	v_lshl_add_u64 v[10:11], s[4:5], 0, v[12:13]
	global_load_dwordx4 v[58:61], v[8:9], off
	global_load_dwordx4 v[62:65], v[10:11], off
	s_waitcnt lgkmcnt(0)
	v_mfma_f32_32x32x16_bf16 v[16:31], v[0:3], v[100:103], v[16:31]
	v_or_b32_e32 v0, 0xe0, v180
	v_bitop3_b32 v0, v0, v66, v67 bitop3:0xde
	v_add_u32_e32 v214, 0, v0
	ds_read_b128 v[0:3], v214 offset:32768
	v_mfma_f32_32x32x16_bf16 v[32:47], v[4:7], v[104:107], v[32:47]
	v_and_b32_e32 v4, 32, v70
	v_and_b32_e32 v5, 0x100, v68
	v_or3_b32 v75, v69, v4, v5
	ds_read_b128 v[4:7], v213 offset:40960
	ds_read_b128 v[66:69], v214 offset:40960
	v_lshlrev_b64 v[70:71], 9, v[192:193]
	v_or_b32_e32 v70, v70, v72
	s_waitcnt lgkmcnt(1)
	v_mfma_f32_32x32x16_bf16 v[32:47], v[4:7], v[100:103], v[32:47]
	v_add_u32_e32 v202, s13, v75
	v_mfma_f32_32x32x16_bf16 v[16:31], v[0:3], v[96:99], v[16:31]
	v_mov_b64_e32 v[0:1], s[68:69]
	v_mov_b64_e32 v[14:15], s[82:83]
	v_mov_b64_e32 v[2:3], s[70:71]
	v_mov_b64_e32 v[4:5], s[72:73]
	v_mov_b64_e32 v[6:7], s[74:75]
	v_mov_b64_e32 v[8:9], s[76:77]
	v_mov_b64_e32 v[10:11], s[78:79]
	s_waitcnt lgkmcnt(0)
	v_mfma_f32_32x32x16_bf16 v[32:47], v[66:69], v[96:99], v[32:47]
	s_nop 2
	v_max_f32_e32 v66, v17, v17
	v_max_f32_e32 v67, v16, v16
	v_max_f32_e32 v66, v67, v66
	v_max3_f32 v66, v66, v18, v19
	v_max3_f32 v66, v66, v20, v21
	v_max3_f32 v66, v66, v22, v23
	v_max3_f32 v66, v66, v24, v25
	v_max3_f32 v66, v66, v26, v27
	v_max3_f32 v66, v66, v28, v29
	v_max3_f32 v66, v66, v30, v31
	v_max3_f32 v66, v66, v32, v33
	v_max3_f32 v66, v66, v34, v35
	v_max3_f32 v66, v66, v36, v37
	v_max3_f32 v66, v66, v38, v39
	v_max3_f32 v66, v66, v40, v41
	v_max3_f32 v66, v66, v42, v43
	v_max3_f32 v66, v66, v44, v45
	v_max3_f32 v76, v66, v46, v47
	v_lshlrev_b64 v[66:67], 9, v[190:191]
	v_or_b32_e32 v66, v66, v72
	v_lshl_add_u64 v[68:69], s[10:11], 0, v[66:67]
	v_lshl_add_u64 v[66:67], s[4:5], 0, v[66:67]
	v_lshl_add_u64 v[72:73], s[10:11], 0, v[70:71]
	global_load_dwordx4 v[128:131], v[68:69], off
	global_load_dwordx4 v[136:139], v[72:73], off
	v_lshl_add_u64 v[68:69], s[4:5], 0, v[70:71]
	global_load_dwordx4 v[132:135], v[66:67], off
	global_load_dwordx4 v[140:143], v[68:69], off
	v_mov_b32_e32 v77, v76
	s_nop 1
	v_permlane32_swap_b32_e32 v76, v77
	v_max_f32_e32 v66, v77, v77
	v_max_f32_e32 v67, v76, v76
	v_max_f32_e32 v66, v67, v66
	s_waitcnt vmcnt(4)
; #define SWRITE(b, i) do { *(bf16x8*)((char*)V_lds + (b) * SHM_V + vst0) = sr_[i].vs0;          \
;     *(bf16x8*)((char*)V_lds + (b) * SHM_V + vst1) = sr_[i].vs1; int kc = sc * 2;               \
;     *(bf16x8*)((char*)K_lds + (b) * SHM_K + KSWZ(sr, kc)) = sr_[i].ks0;                       \
;     *(bf16x8*)((char*)K_lds + (b) * SHM_K + KSWZ(32 + sr, kc)) = sr_[i].ks1; } while (0)
; #define SWAIT() asm volatile("s_waitcnt vmcnt(4)" ::: "memory")
; DI void partialSM(f32x16& p0, f32x16& p1, float& m_reg, float& mn, float& alpha) {
;   constexpr float C = SCALE * 1.4426950408889634f;
;   float pmax = p0[0]; for (int r = 1; r < 16; ++r) pmax = fmaxf(pmax, p0[r]); for (int r = 0; r < 16; ++r) pmax = fmaxf(pmax, p1[r]);
;   { auto rr = __builtin_amdgcn_permlane32_swap(__float_as_uint(pmax), __float_as_uint(pmax), false, false);
;     pmax = fmaxf(__uint_as_float(rr[0]), __uint_as_float(rr[1])); }
;   if (__builtin_expect(__all(pmax - m_reg <= THR / SCALE), 1)) { mn = m_reg; alpha = 1.f; }
;   else { mn = fmaxf(m_reg, pmax); alpha = __builtin_amdgcn_exp2f((m_reg - mn) * C); m_reg = mn; }
;   float mnC = -mn * C;
;   for (int r = 0; r < 16; ++r) p0[r] = fmaf(p0[r], C, mnC); for (int r = 0; r < 16; ++r) p1[r] = fmaf(p1[r], C, mnC);
;   for (int r = 0; r < 16; ++r) p0[r] = __builtin_amdgcn_exp2f(p0[r]);
; DI void attn_dense_body(const bf16_t* __restrict__ Qb, const bf16_t* __restrict__ Kh, const bf16_t* __restrict__ Vh, ...
;     ...
;   SWAIT(); SWRITE(1, SO); __syncthreads();
	s_waitcnt vmcnt(7)
	ds_write_b128 v204, v[50:53] offset:16384
	s_waitcnt vmcnt(6)
	ds_write_b128 v205, v[54:57] offset:16384
	s_waitcnt vmcnt(5)
	ds_write_b128 v203, v[58:61] offset:49152
	s_waitcnt vmcnt(4)
	ds_write_b128 v206, v[62:65] offset:49152
	v_max_f32_e32 v50, 0xf149f2ca, v66
	v_sub_f32_e32 v51, 0xf149f2ca, v50
	v_mul_f32_e32 v51, 0x3e0293ee, v51
	v_add_f32_e32 v67, 0x7149f2ca, v66
	v_exp_f32_e32 v51, v51
	v_cmp_ge_f32_e32 vcc, s95, v67
	s_cmp_eq_u64 vcc, exec
	s_cselect_b64 vcc, -1, 0
	v_cndmask_b32_e64 v215, v51, 1.0, vcc
	v_mov_b32_e32 v51, 0xf149f2ca
	v_cndmask_b32_e32 v168, v50, v51, vcc
	v_mul_f32_e32 v50, 0xbe0293ee, v168
	v_fmamk_f32 v16, v16, 0x3e0293ee, v50
	v_exp_f32_e32 v161, v16
	v_fmamk_f32 v16, v17, 0x3e0293ee, v50
	v_exp_f32_e32 v175, v16
	v_fmamk_f32 v16, v18, 0x3e0293ee, v50
	v_exp_f32_e32 v162, v16
	v_fmamk_f32 v16, v19, 0x3e0293ee, v50
	v_exp_f32_e32 v219, v16
	v_fmamk_f32 v16, v20, 0x3e0293ee, v50
	v_exp_f32_e32 v174, v16
	v_fmamk_f32 v16, v21, 0x3e0293ee, v50
	v_exp_f32_e32 v222, v16
	v_fmamk_f32 v16, v22, 0x3e0293ee, v50
	v_exp_f32_e32 v163, v16
	v_fmamk_f32 v16, v23, 0x3e0293ee, v50
	v_exp_f32_e32 v173, v16
	v_fmamk_f32 v16, v24, 0x3e0293ee, v50
	v_exp_f32_e32 v164, v16
	v_fmamk_f32 v16, v25, 0x3e0293ee, v50
	v_exp_f32_e32 v171, v16
	v_fmamk_f32 v16, v26, 0x3e0293ee, v50
	v_exp_f32_e32 v165, v16
	v_fmamk_f32 v16, v27, 0x3e0293ee, v50
	s_addk_i32 s13, 0x4000
	v_exp_f32_e32 v172, v16
	v_fmamk_f32 v16, v28, 0x3e0293ee, v50
	s_add_u32 s0, s0, s12
	v_exp_f32_e32 v166, v16
	v_fmamk_f32 v16, v29, 0x3e0293ee, v50
	s_addc_u32 s1, s1, 0
	v_pk_fma_f32 v[144:145], v[46:47], s[42:43], v[50:51] op_sel_hi:[1,0,0]
	v_pk_fma_f32 v[150:151], v[44:45], s[42:43], v[50:51] op_sel_hi:[1,0,0]
	v_pk_fma_f32 v[154:155], v[42:43], s[42:43], v[50:51] op_sel_hi:[1,0,0]
	v_pk_fma_f32 v[146:147], v[40:41], s[42:43], v[50:51] op_sel_hi:[1,0,0]
	v_pk_fma_f32 v[148:149], v[38:39], s[42:43], v[50:51] op_sel_hi:[1,0,0]
	v_pk_fma_f32 v[152:153], v[36:37], s[42:43], v[50:51] op_sel_hi:[1,0,0]
	v_pk_fma_f32 v[156:157], v[34:35], s[42:43], v[50:51] op_sel_hi:[1,0,0]
	v_pk_fma_f32 v[158:159], v[32:33], s[42:43], v[50:51] op_sel_hi:[1,0,0]
	v_exp_f32_e32 v169, v16
	v_fmamk_f32 v16, v30, 0x3e0293ee, v50
	v_fmac_f32_e32 v50, 0x3e0293ee, v31
	s_lshl_b64 s[0:1], s[0:1], 1
	v_readlane_b32 s10, v255, 31
	v_exp_f32_e32 v167, v16
	v_exp_f32_e32 v170, v50
	v_and_b32_e32 v16, 15, v160
	s_add_u32 s0, s10, s0
	v_readlane_b32 s10, v255, 32
	v_lshl_or_b32 v48, v16, 4, v48
	s_addc_u32 s1, s10, s1
	v_mov_b64_e32 v[12:13], s[80:81]
	v_lshl_add_u64 v[194:195], s[0:1], 0, v[48:49]
	v_mov_b64_e32 v[62:63], v[14:15]
	v_mov_b64_e32 v[46:47], v[14:15]
	v_mov_b64_e32 v[30:31], v[14:15]
	v_cmp_gt_u32_e64 s[4:5], 32, v74
	v_add_u32_e32 v201, s13, v75
	v_mov_b64_e32 v[60:61], v[12:13]
	v_mov_b64_e32 v[58:59], v[10:11]
	v_mov_b64_e32 v[56:57], v[8:9]
	v_mov_b64_e32 v[54:55], v[6:7]
	v_mov_b64_e32 v[52:53], v[4:5]
	v_mov_b64_e32 v[50:51], v[2:3]
	v_mov_b64_e32 v[48:49], v[0:1]
	v_mov_b64_e32 v[44:45], v[12:13]
	v_mov_b64_e32 v[42:43], v[10:11]
	v_mov_b64_e32 v[40:41], v[8:9]
	v_mov_b64_e32 v[38:39], v[6:7]
	v_mov_b64_e32 v[36:37], v[4:5]
	v_mov_b64_e32 v[34:35], v[2:3]
	v_mov_b64_e32 v[32:33], v[0:1]
	v_mov_b64_e32 v[28:29], v[12:13]
	v_mov_b64_e32 v[26:27], v[10:11]
	v_mov_b64_e32 v[24:25], v[8:9]
	v_mov_b64_e32 v[22:23], v[6:7]
	v_mov_b64_e32 v[20:21], v[4:5]
	v_mov_b64_e32 v[18:19], v[2:3]
	v_mov_b64_e32 v[16:17], v[0:1]
	v_readfirstlane_b32 s100, v252
	s_nop 3
	s_lshr_b32 s100, s100, 6
	s_cmp_ge_u32 s100, 4
	s_cbranch_scc1 .Lattn_prio_done
	s_setprio 1
